# combination: no-op-scale-free ffup reciprocal refinement + deferred first read-back, odin V-segment fast path, LDS-staged dwordx4 EpiResid for the split-K instances (on top of the ev_out prefetch vers
# speedup vs baseline: 1.0113x; 1.0081x over previous
.LBB0_1034:
	v_lshl_or_b32 v115, v183, 3, v191
	v_lshrrev_b32_e32 v116, 6, v115
	v_and_b32_e32 v117, 63, v115
	v_lshlrev_b32_e32 v113, 11, v116
	v_add_u32_e32 v113, 0x10000, v113
	v_readfirstlane_b32 s100, v116
	v_and_b32_e32 v112, 31, v117
	v_lshl_add_u32 v112, v112, 1, v113
	v_lshrrev_b32_e32 v116, 5, v117
	v_lshl_add_u32 v112, v116, 8, v112
	v_lshl_add_u32 v113, v117, 4, v113
	v_lshrrev_b32_e32 v116, 2, v117
	v_mul_u32_u24_e32 v116, 0x1600, v116
	v_and_b32_e32 v114, 3, v117
	v_lshl_add_u32 v114, v114, 4, v116
	s_lshr_b32 s101, s100, 1
	s_lshl_b32 s101, s101, 6
	s_add_u32 s101, s101, s48
	s_mul_i32 s101, s101, 0x1600
	s_and_b32 s100, s100, 1
	s_lshl_b32 s100, s100, 6
	s_add_u32 s100, s100, s49
	s_add_u32 s101, s101, s100
	s_add_u32 s98, s90, 0x3971900
	s_addc_u32 s99, s91, 0
	s_add_u32 s98, s98, s101
	s_addc_u32 s99, s99, 0
	v_mul_f32_e32 v64, 0xbfb8aa3b, v48
	v_mul_f32_e32 v70, 0xbfb8aa3b, v49
	v_mul_f32_e32 v76, 0xbfb8aa3b, v50
	v_mul_f32_e32 v82, 0xbfb8aa3b, v51
	v_exp_f32_e32 v64, v64
	v_exp_f32_e32 v70, v70
	v_exp_f32_e32 v76, v76
	v_exp_f32_e32 v82, v82
	v_add_f32_e32 v64, 1.0, v64
	v_add_f32_e32 v70, 1.0, v70
	v_add_f32_e32 v76, 1.0, v76
	v_add_f32_e32 v82, 1.0, v82
	v_rcp_f32_e32 v66, v64
	v_rcp_f32_e32 v72, v70
	v_rcp_f32_e32 v78, v76
	v_rcp_f32_e32 v84, v82
	v_fma_f32 v69, -v64, v66, 1.0
	v_fma_f32 v75, -v70, v72, 1.0
	v_fma_f32 v81, -v76, v78, 1.0
	v_fma_f32 v87, -v82, v84, 1.0
	v_fmac_f32_e32 v66, v69, v66
	v_fmac_f32_e32 v72, v75, v72
	v_fmac_f32_e32 v78, v81, v78
	v_fmac_f32_e32 v84, v87, v84
	v_fma_f32 v69, -v64, v66, 1.0
	v_mul_f32_e32 v88, 0xbfb8aa3b, v52
	v_fma_f32 v75, -v70, v72, 1.0
	v_mul_f32_e32 v94, 0xbfb8aa3b, v53
	v_fma_f32 v81, -v76, v78, 1.0
	v_mul_f32_e32 v100, 0xbfb8aa3b, v54
	v_fma_f32 v87, -v82, v84, 1.0
	v_mul_f32_e32 v106, 0xbfb8aa3b, v55
	v_fma_f32 v68, v69, v66, v66
	v_exp_f32_e32 v88, v88
	v_fma_f32 v74, v75, v72, v72
	v_exp_f32_e32 v94, v94
	v_fma_f32 v80, v81, v78, v78
	v_exp_f32_e32 v100, v100
	v_fma_f32 v86, v87, v84, v84
	v_exp_f32_e32 v106, v106
	v_fma_f32 v69, -v64, v68, 1.0
	v_add_f32_e32 v88, 1.0, v88
	v_fma_f32 v75, -v70, v74, 1.0
	v_add_f32_e32 v94, 1.0, v94
	v_fma_f32 v81, -v76, v80, 1.0
	v_add_f32_e32 v100, 1.0, v100
	v_fma_f32 v87, -v82, v86, 1.0
	v_add_f32_e32 v106, 1.0, v106
	v_fma_f32 v65, v69, v66, v68
	v_rcp_f32_e32 v90, v88
	v_fma_f32 v71, v75, v72, v74
	v_rcp_f32_e32 v96, v94
	v_fma_f32 v77, v81, v78, v80
	v_rcp_f32_e32 v102, v100
	v_fma_f32 v83, v87, v84, v86
	v_rcp_f32_e32 v108, v106
	v_fma_f32 v93, -v88, v90, 1.0
	v_fma_f32 v99, -v94, v96, 1.0
	v_fma_f32 v105, -v100, v102, 1.0
	v_fma_f32 v111, -v106, v108, 1.0
	v_fmac_f32_e32 v90, v93, v90
	v_fmac_f32_e32 v96, v99, v96
	v_fmac_f32_e32 v102, v105, v102
	v_fmac_f32_e32 v108, v111, v108
	v_div_fixup_f32 v65, v65, v64, 1.0
	v_div_fixup_f32 v71, v71, v70, 1.0
	v_div_fixup_f32 v77, v77, v76, 1.0
	v_div_fixup_f32 v83, v83, v82, 1.0
	v_mul_f32_e32 v65, v48, v65
	v_mul_f32_e32 v71, v49, v71
	v_mul_f32_e32 v77, v50, v77
	v_mul_f32_e32 v83, v51, v83
	v_mul_f32_e32 v65, v32, v65
	v_mul_f32_e32 v71, v33, v71
	v_mul_f32_e32 v77, v34, v77
	v_mul_f32_e32 v83, v35, v83
	v_cvt_pk_bf16_f32 v65, v65, v65
	v_cvt_pk_bf16_f32 v71, v71, v71
	v_cvt_pk_bf16_f32 v77, v77, v77
	v_cvt_pk_bf16_f32 v83, v83, v83
	ds_write_b16 v112, v65
	ds_write_b16 v112, v71 offset:64
	ds_write_b16 v112, v77 offset:128
	ds_write_b16 v112, v83 offset:192
	v_fma_f32 v93, -v88, v90, 1.0
	v_mul_f32_e32 v64, 0xbfb8aa3b, v56
	v_fma_f32 v99, -v94, v96, 1.0
	v_mul_f32_e32 v70, 0xbfb8aa3b, v57
	v_fma_f32 v105, -v100, v102, 1.0
	v_mul_f32_e32 v76, 0xbfb8aa3b, v58
	v_fma_f32 v111, -v106, v108, 1.0
	v_mul_f32_e32 v82, 0xbfb8aa3b, v59
	v_fma_f32 v92, v93, v90, v90
	v_exp_f32_e32 v64, v64
	v_fma_f32 v98, v99, v96, v96
	v_exp_f32_e32 v70, v70
	v_fma_f32 v104, v105, v102, v102
	v_exp_f32_e32 v76, v76
	v_fma_f32 v110, v111, v108, v108
	v_exp_f32_e32 v82, v82
	v_fma_f32 v93, -v88, v92, 1.0
	v_add_f32_e32 v64, 1.0, v64
	v_fma_f32 v99, -v94, v98, 1.0
	v_add_f32_e32 v70, 1.0, v70
	v_fma_f32 v105, -v100, v104, 1.0
	v_add_f32_e32 v76, 1.0, v76
	v_fma_f32 v111, -v106, v110, 1.0
	v_add_f32_e32 v82, 1.0, v82
	v_fma_f32 v89, v93, v90, v92
	v_rcp_f32_e32 v66, v64
	v_fma_f32 v95, v99, v96, v98
	v_rcp_f32_e32 v72, v70
	v_fma_f32 v101, v105, v102, v104
	v_rcp_f32_e32 v78, v76
	v_fma_f32 v107, v111, v108, v110
	v_rcp_f32_e32 v84, v82
	v_fma_f32 v69, -v64, v66, 1.0
	v_fma_f32 v75, -v70, v72, 1.0
	v_fma_f32 v81, -v76, v78, 1.0
	v_fma_f32 v87, -v82, v84, 1.0
	v_fmac_f32_e32 v66, v69, v66
	v_fmac_f32_e32 v72, v75, v72
	v_fmac_f32_e32 v78, v81, v78
	v_fmac_f32_e32 v84, v87, v84
	v_div_fixup_f32 v89, v89, v88, 1.0
	v_div_fixup_f32 v95, v95, v94, 1.0
	v_div_fixup_f32 v101, v101, v100, 1.0
	v_div_fixup_f32 v107, v107, v106, 1.0
	v_mul_f32_e32 v89, v52, v89
	v_mul_f32_e32 v95, v53, v95
	v_mul_f32_e32 v101, v54, v101
	v_mul_f32_e32 v107, v55, v107
	v_mul_f32_e32 v89, v36, v89
	v_mul_f32_e32 v95, v37, v95
	v_mul_f32_e32 v101, v38, v101
	v_mul_f32_e32 v107, v39, v107
	v_cvt_pk_bf16_f32 v89, v89, v89
	v_cvt_pk_bf16_f32 v95, v95, v95
	v_cvt_pk_bf16_f32 v101, v101, v101
	v_cvt_pk_bf16_f32 v107, v107, v107
	ds_write_b16 v112, v89 offset:512
	ds_write_b16 v112, v95 offset:576
	ds_write_b16 v112, v101 offset:640
	ds_write_b16 v112, v107 offset:704
	v_fma_f32 v69, -v64, v66, 1.0
	v_mul_f32_e32 v88, 0xbfb8aa3b, v60
	v_fma_f32 v75, -v70, v72, 1.0
	v_mul_f32_e32 v94, 0xbfb8aa3b, v61
	v_fma_f32 v81, -v76, v78, 1.0
	v_mul_f32_e32 v100, 0xbfb8aa3b, v62
	v_fma_f32 v87, -v82, v84, 1.0
	v_mul_f32_e32 v106, 0xbfb8aa3b, v63
	v_fma_f32 v68, v69, v66, v66
	v_exp_f32_e32 v88, v88
	v_fma_f32 v74, v75, v72, v72
	v_exp_f32_e32 v94, v94
	v_fma_f32 v80, v81, v78, v78
	v_exp_f32_e32 v100, v100
	v_fma_f32 v86, v87, v84, v84
	v_exp_f32_e32 v106, v106
	v_fma_f32 v69, -v64, v68, 1.0
	v_add_f32_e32 v88, 1.0, v88
	v_fma_f32 v75, -v70, v74, 1.0
	v_add_f32_e32 v94, 1.0, v94
	v_fma_f32 v81, -v76, v80, 1.0
	v_add_f32_e32 v100, 1.0, v100
	v_fma_f32 v87, -v82, v86, 1.0
	v_add_f32_e32 v106, 1.0, v106
	v_fma_f32 v65, v69, v66, v68
	v_rcp_f32_e32 v90, v88
	v_fma_f32 v71, v75, v72, v74
	v_rcp_f32_e32 v96, v94
	v_fma_f32 v77, v81, v78, v80
	v_rcp_f32_e32 v102, v100
	v_fma_f32 v83, v87, v84, v86
	v_rcp_f32_e32 v108, v106
	v_fma_f32 v93, -v88, v90, 1.0
	v_fma_f32 v99, -v94, v96, 1.0
	v_fma_f32 v105, -v100, v102, 1.0
	v_fma_f32 v111, -v106, v108, 1.0
	v_fmac_f32_e32 v90, v93, v90
	v_fmac_f32_e32 v96, v99, v96
	v_fmac_f32_e32 v102, v105, v102
	v_fmac_f32_e32 v108, v111, v108
	v_div_fixup_f32 v65, v65, v64, 1.0
	v_div_fixup_f32 v71, v71, v70, 1.0
	v_div_fixup_f32 v77, v77, v76, 1.0
	v_div_fixup_f32 v83, v83, v82, 1.0
	v_mul_f32_e32 v65, v56, v65
	v_mul_f32_e32 v71, v57, v71
	v_mul_f32_e32 v77, v58, v77
	v_mul_f32_e32 v83, v59, v83
	v_mul_f32_e32 v65, v40, v65
	v_mul_f32_e32 v71, v41, v71
	v_mul_f32_e32 v77, v42, v77
	v_mul_f32_e32 v83, v43, v83
	v_cvt_pk_bf16_f32 v65, v65, v65
	v_cvt_pk_bf16_f32 v71, v71, v71
	v_cvt_pk_bf16_f32 v77, v77, v77
	v_cvt_pk_bf16_f32 v83, v83, v83
	ds_write_b16 v112, v65 offset:1024
	ds_write_b16 v112, v71 offset:1088
	ds_write_b16 v112, v77 offset:1152
	ds_write_b16 v112, v83 offset:1216
	v_fma_f32 v93, -v88, v90, 1.0
	v_mul_f32_e32 v64, 0xbfb8aa3b, v16
	v_fma_f32 v99, -v94, v96, 1.0
	v_mul_f32_e32 v70, 0xbfb8aa3b, v17
	v_fma_f32 v105, -v100, v102, 1.0
	v_mul_f32_e32 v76, 0xbfb8aa3b, v18
	v_fma_f32 v111, -v106, v108, 1.0
	v_mul_f32_e32 v82, 0xbfb8aa3b, v19
	v_fma_f32 v92, v93, v90, v90
	v_exp_f32_e32 v64, v64
	v_fma_f32 v98, v99, v96, v96
	v_exp_f32_e32 v70, v70
	v_fma_f32 v104, v105, v102, v102
	v_exp_f32_e32 v76, v76
	v_fma_f32 v110, v111, v108, v108
	v_exp_f32_e32 v82, v82
	v_fma_f32 v93, -v88, v92, 1.0
	v_add_f32_e32 v64, 1.0, v64
	v_fma_f32 v99, -v94, v98, 1.0
	v_add_f32_e32 v70, 1.0, v70
	v_fma_f32 v105, -v100, v104, 1.0
	v_add_f32_e32 v76, 1.0, v76
	v_fma_f32 v111, -v106, v110, 1.0
	v_add_f32_e32 v82, 1.0, v82
	v_fma_f32 v89, v93, v90, v92
	v_rcp_f32_e32 v66, v64
	v_fma_f32 v95, v99, v96, v98
	v_rcp_f32_e32 v72, v70
	v_fma_f32 v101, v105, v102, v104
	v_rcp_f32_e32 v78, v76
	v_fma_f32 v107, v111, v108, v110
	v_rcp_f32_e32 v84, v82
	v_fma_f32 v69, -v64, v66, 1.0
	v_fma_f32 v75, -v70, v72, 1.0
	v_fma_f32 v81, -v76, v78, 1.0
	v_fma_f32 v87, -v82, v84, 1.0
	v_fmac_f32_e32 v66, v69, v66
	v_fmac_f32_e32 v72, v75, v72
	v_fmac_f32_e32 v78, v81, v78
	v_fmac_f32_e32 v84, v87, v84
	v_div_fixup_f32 v89, v89, v88, 1.0
	v_div_fixup_f32 v95, v95, v94, 1.0
	v_div_fixup_f32 v101, v101, v100, 1.0
	v_div_fixup_f32 v107, v107, v106, 1.0
	v_mul_f32_e32 v89, v60, v89
	v_mul_f32_e32 v95, v61, v95
	v_mul_f32_e32 v101, v62, v101
	v_mul_f32_e32 v107, v63, v107
	v_mul_f32_e32 v89, v44, v89
	v_mul_f32_e32 v95, v45, v95
	v_mul_f32_e32 v101, v46, v101
	v_mul_f32_e32 v107, v47, v107
	v_cvt_pk_bf16_f32 v89, v89, v89
	v_cvt_pk_bf16_f32 v95, v95, v95
	v_cvt_pk_bf16_f32 v101, v101, v101
	v_cvt_pk_bf16_f32 v107, v107, v107
	ds_write_b16 v112, v89 offset:1536
	ds_write_b16 v112, v95 offset:1600
	ds_write_b16 v112, v101 offset:1664
	ds_write_b16 v112, v107 offset:1728
	ds_read_b128 v[120:123], v113
	ds_read_b128 v[124:127], v113 offset:1024
	v_fma_f32 v69, -v64, v66, 1.0
	v_mul_f32_e32 v88, 0xbfb8aa3b, v20
	v_fma_f32 v75, -v70, v72, 1.0
	v_mul_f32_e32 v94, 0xbfb8aa3b, v21
	v_fma_f32 v81, -v76, v78, 1.0
	v_mul_f32_e32 v100, 0xbfb8aa3b, v22
	v_fma_f32 v87, -v82, v84, 1.0
	v_mul_f32_e32 v106, 0xbfb8aa3b, v23
	v_fma_f32 v68, v69, v66, v66
	v_exp_f32_e32 v88, v88
	v_fma_f32 v74, v75, v72, v72
	v_exp_f32_e32 v94, v94
	v_fma_f32 v80, v81, v78, v78
	v_exp_f32_e32 v100, v100
	v_fma_f32 v86, v87, v84, v84
	v_exp_f32_e32 v106, v106
	v_fma_f32 v69, -v64, v68, 1.0
	v_add_f32_e32 v88, 1.0, v88
	v_fma_f32 v75, -v70, v74, 1.0
	v_add_f32_e32 v94, 1.0, v94
	v_fma_f32 v81, -v76, v80, 1.0
	v_add_f32_e32 v100, 1.0, v100
	v_fma_f32 v87, -v82, v86, 1.0
	v_add_f32_e32 v106, 1.0, v106
	v_fma_f32 v65, v69, v66, v68
	v_rcp_f32_e32 v90, v88
	v_fma_f32 v71, v75, v72, v74
	v_rcp_f32_e32 v96, v94
	v_fma_f32 v77, v81, v78, v80
	v_rcp_f32_e32 v102, v100
	v_fma_f32 v83, v87, v84, v86
	v_rcp_f32_e32 v108, v106
	v_fma_f32 v93, -v88, v90, 1.0
	v_fma_f32 v99, -v94, v96, 1.0
	v_fma_f32 v105, -v100, v102, 1.0
	v_fma_f32 v111, -v106, v108, 1.0
	v_fmac_f32_e32 v90, v93, v90
	v_fmac_f32_e32 v96, v99, v96
	v_fmac_f32_e32 v102, v105, v102
	v_fmac_f32_e32 v108, v111, v108
	v_div_fixup_f32 v65, v65, v64, 1.0
	v_div_fixup_f32 v71, v71, v70, 1.0
	v_div_fixup_f32 v77, v77, v76, 1.0
	v_div_fixup_f32 v83, v83, v82, 1.0
	v_mul_f32_e32 v65, v16, v65
	v_mul_f32_e32 v71, v17, v71
	v_mul_f32_e32 v77, v18, v77
	v_mul_f32_e32 v83, v19, v83
	v_mul_f32_e32 v65, v0, v65
	v_mul_f32_e32 v71, v1, v71
	v_mul_f32_e32 v77, v2, v77
	v_mul_f32_e32 v83, v3, v83
	v_cvt_pk_bf16_f32 v65, v65, v65
	v_cvt_pk_bf16_f32 v71, v71, v71
	v_cvt_pk_bf16_f32 v77, v77, v77
	v_cvt_pk_bf16_f32 v83, v83, v83
	ds_write_b16 v112, v65
	ds_write_b16 v112, v71 offset:64
	ds_write_b16 v112, v77 offset:128
	ds_write_b16 v112, v83 offset:192
	v_fma_f32 v93, -v88, v90, 1.0
	v_mul_f32_e32 v64, 0xbfb8aa3b, v24
	v_fma_f32 v99, -v94, v96, 1.0
	v_mul_f32_e32 v70, 0xbfb8aa3b, v25
	v_fma_f32 v105, -v100, v102, 1.0
	v_mul_f32_e32 v76, 0xbfb8aa3b, v26
	v_fma_f32 v111, -v106, v108, 1.0
	v_mul_f32_e32 v82, 0xbfb8aa3b, v27
	v_fma_f32 v92, v93, v90, v90
	v_exp_f32_e32 v64, v64
	v_fma_f32 v98, v99, v96, v96
	v_exp_f32_e32 v70, v70
	v_fma_f32 v104, v105, v102, v102
	v_exp_f32_e32 v76, v76
	v_fma_f32 v110, v111, v108, v108
	v_exp_f32_e32 v82, v82
	v_fma_f32 v93, -v88, v92, 1.0
	v_add_f32_e32 v64, 1.0, v64
	v_fma_f32 v99, -v94, v98, 1.0
	v_add_f32_e32 v70, 1.0, v70
	v_fma_f32 v105, -v100, v104, 1.0
	v_add_f32_e32 v76, 1.0, v76
	v_fma_f32 v111, -v106, v110, 1.0
	v_add_f32_e32 v82, 1.0, v82
	v_fma_f32 v89, v93, v90, v92
	v_rcp_f32_e32 v66, v64
	v_fma_f32 v95, v99, v96, v98
	v_rcp_f32_e32 v72, v70
	v_fma_f32 v101, v105, v102, v104
	v_rcp_f32_e32 v78, v76
	v_fma_f32 v107, v111, v108, v110
	v_rcp_f32_e32 v84, v82
	v_fma_f32 v69, -v64, v66, 1.0
	v_fma_f32 v75, -v70, v72, 1.0
	v_fma_f32 v81, -v76, v78, 1.0
	v_fma_f32 v87, -v82, v84, 1.0
	v_fmac_f32_e32 v66, v69, v66
	v_fmac_f32_e32 v72, v75, v72
	v_fmac_f32_e32 v78, v81, v78
	v_fmac_f32_e32 v84, v87, v84
	s_waitcnt lgkmcnt(0)
	global_store_dwordx4 v114, v[120:123], s[98:99]
	s_add_u32 s98, s98, 0x16000
	s_addc_u32 s99, s99, 0
	global_store_dwordx4 v114, v[124:127], s[98:99]
	s_add_u32 s98, s98, 0x16000
	s_addc_u32 s99, s99, 0
	v_div_fixup_f32 v89, v89, v88, 1.0
	v_div_fixup_f32 v95, v95, v94, 1.0
	v_div_fixup_f32 v101, v101, v100, 1.0
	v_div_fixup_f32 v107, v107, v106, 1.0
	v_mul_f32_e32 v89, v20, v89
	v_mul_f32_e32 v95, v21, v95
	v_mul_f32_e32 v101, v22, v101
	v_mul_f32_e32 v107, v23, v107
	v_mul_f32_e32 v89, v4, v89
	v_mul_f32_e32 v95, v5, v95
	v_mul_f32_e32 v101, v6, v101
	v_mul_f32_e32 v107, v7, v107
	v_cvt_pk_bf16_f32 v89, v89, v89
	v_cvt_pk_bf16_f32 v95, v95, v95
	v_cvt_pk_bf16_f32 v101, v101, v101
	v_cvt_pk_bf16_f32 v107, v107, v107
	ds_write_b16 v112, v89 offset:512
	ds_write_b16 v112, v95 offset:576
	ds_write_b16 v112, v101 offset:640
	ds_write_b16 v112, v107 offset:704
	v_fma_f32 v69, -v64, v66, 1.0
	v_mul_f32_e32 v88, 0xbfb8aa3b, v28
	v_fma_f32 v75, -v70, v72, 1.0
	v_mul_f32_e32 v94, 0xbfb8aa3b, v29
	v_fma_f32 v81, -v76, v78, 1.0
	v_mul_f32_e32 v100, 0xbfb8aa3b, v30
	v_fma_f32 v87, -v82, v84, 1.0
	v_mul_f32_e32 v106, 0xbfb8aa3b, v31
	v_fma_f32 v68, v69, v66, v66
	v_exp_f32_e32 v88, v88
	v_fma_f32 v74, v75, v72, v72
	v_exp_f32_e32 v94, v94
	v_fma_f32 v80, v81, v78, v78
	v_exp_f32_e32 v100, v100
	v_fma_f32 v86, v87, v84, v84
	v_exp_f32_e32 v106, v106
	v_fma_f32 v69, -v64, v68, 1.0
	v_add_f32_e32 v88, 1.0, v88
	v_fma_f32 v75, -v70, v74, 1.0
	v_add_f32_e32 v94, 1.0, v94
	v_fma_f32 v81, -v76, v80, 1.0
	v_add_f32_e32 v100, 1.0, v100
	v_fma_f32 v87, -v82, v86, 1.0
	v_add_f32_e32 v106, 1.0, v106
	v_fma_f32 v65, v69, v66, v68
	v_rcp_f32_e32 v90, v88
	v_fma_f32 v71, v75, v72, v74
	v_rcp_f32_e32 v96, v94
	v_fma_f32 v77, v81, v78, v80
	v_rcp_f32_e32 v102, v100
	v_fma_f32 v83, v87, v84, v86
	v_rcp_f32_e32 v108, v106
	v_fma_f32 v93, -v88, v90, 1.0
	v_fma_f32 v99, -v94, v96, 1.0
	v_fma_f32 v105, -v100, v102, 1.0
	v_fma_f32 v111, -v106, v108, 1.0
	v_fmac_f32_e32 v90, v93, v90
	v_fmac_f32_e32 v96, v99, v96
	v_fmac_f32_e32 v102, v105, v102
	v_fmac_f32_e32 v108, v111, v108
	v_div_fixup_f32 v65, v65, v64, 1.0
	v_div_fixup_f32 v71, v71, v70, 1.0
	v_div_fixup_f32 v77, v77, v76, 1.0
	v_div_fixup_f32 v83, v83, v82, 1.0
	v_mul_f32_e32 v65, v24, v65
	v_mul_f32_e32 v71, v25, v71
	v_mul_f32_e32 v77, v26, v77
	v_mul_f32_e32 v83, v27, v83
	v_mul_f32_e32 v65, v8, v65
	v_mul_f32_e32 v71, v9, v71
	v_mul_f32_e32 v77, v10, v77
	v_mul_f32_e32 v83, v11, v83
	v_cvt_pk_bf16_f32 v65, v65, v65
	v_cvt_pk_bf16_f32 v71, v71, v71
	v_cvt_pk_bf16_f32 v77, v77, v77
	v_cvt_pk_bf16_f32 v83, v83, v83
	ds_write_b16 v112, v65 offset:1024
	ds_write_b16 v112, v71 offset:1088
	ds_write_b16 v112, v77 offset:1152
	ds_write_b16 v112, v83 offset:1216
	v_fma_f32 v93, -v88, v90, 1.0
	v_fma_f32 v99, -v94, v96, 1.0
	v_fma_f32 v105, -v100, v102, 1.0
	v_fma_f32 v111, -v106, v108, 1.0
	v_fma_f32 v92, v93, v90, v90
	v_fma_f32 v98, v99, v96, v96
	v_fma_f32 v104, v105, v102, v102
	v_fma_f32 v110, v111, v108, v108
	v_fma_f32 v93, -v88, v92, 1.0
	v_fma_f32 v99, -v94, v98, 1.0
	v_fma_f32 v105, -v100, v104, 1.0
	v_fma_f32 v111, -v106, v110, 1.0
	v_fma_f32 v89, v93, v90, v92
	v_fma_f32 v95, v99, v96, v98
	v_fma_f32 v101, v105, v102, v104
	v_fma_f32 v107, v111, v108, v110
	v_div_fixup_f32 v89, v89, v88, 1.0
	v_div_fixup_f32 v95, v95, v94, 1.0
	v_div_fixup_f32 v101, v101, v100, 1.0
	v_div_fixup_f32 v107, v107, v106, 1.0
	v_mul_f32_e32 v89, v28, v89
	v_mul_f32_e32 v95, v29, v95
	v_mul_f32_e32 v101, v30, v101
	v_mul_f32_e32 v107, v31, v107
	v_mul_f32_e32 v89, v12, v89
	v_mul_f32_e32 v95, v13, v95
	v_mul_f32_e32 v101, v14, v101
	v_mul_f32_e32 v107, v15, v107
	v_cvt_pk_bf16_f32 v89, v89, v89
	v_cvt_pk_bf16_f32 v95, v95, v95
	v_cvt_pk_bf16_f32 v101, v101, v101
	v_cvt_pk_bf16_f32 v107, v107, v107
	ds_write_b16 v112, v89 offset:1536
	ds_write_b16 v112, v95 offset:1600
	ds_write_b16 v112, v101 offset:1664
	ds_write_b16 v112, v107 offset:1728
	ds_read_b128 v[120:123], v113
	ds_read_b128 v[124:127], v113 offset:1024
	s_waitcnt lgkmcnt(0)
	global_store_dwordx4 v114, v[120:123], s[98:99]
	s_add_u32 s98, s98, 0x16000
	s_addc_u32 s99, s99, 0
	global_store_dwordx4 v114, v[124:127], s[98:99]
	s_add_u32 s98, s98, 0x16000
	s_addc_u32 s99, s99, 0
	s_add_i32 s57, s57, s92
	s_cmpk_gt_i32 s57, 0x107f
	s_cbranch_scc1 .LBB0_1043

.LBB0_2283:
	v_lshl_or_b32 v115, v183, 3, v191
	v_lshrrev_b32_e32 v116, 6, v115
	v_and_b32_e32 v117, 63, v115
	v_lshlrev_b32_e32 v113, 11, v116
	v_add_u32_e32 v113, 0x10000, v113
	v_readfirstlane_b32 s100, v116
	v_and_b32_e32 v112, 31, v117
	v_lshl_add_u32 v112, v112, 1, v113
	v_lshrrev_b32_e32 v116, 5, v117
	v_lshl_add_u32 v112, v116, 8, v112
	v_lshl_add_u32 v113, v117, 4, v113
	v_lshrrev_b32_e32 v116, 2, v117
	v_mul_u32_u24_e32 v116, 0x1600, v116
	v_and_b32_e32 v114, 3, v117
	v_lshl_add_u32 v114, v114, 4, v116
	s_lshr_b32 s101, s100, 1
	s_lshl_b32 s101, s101, 6
	s_add_u32 s101, s101, s48
	s_mul_i32 s101, s101, 0x1600
	s_and_b32 s100, s100, 1
	s_lshl_b32 s100, s100, 6
	s_add_u32 s100, s100, s49
	s_add_u32 s101, s101, s100
	s_add_u32 s98, s90, 0x3971900
	s_addc_u32 s99, s91, 0
	s_add_u32 s98, s98, s101
	s_addc_u32 s99, s99, 0
	v_mul_f32_e32 v64, 0xbfb8aa3b, v48
	v_mul_f32_e32 v70, 0xbfb8aa3b, v49
	v_mul_f32_e32 v76, 0xbfb8aa3b, v50
	v_mul_f32_e32 v82, 0xbfb8aa3b, v51
	v_exp_f32_e32 v64, v64
	v_exp_f32_e32 v70, v70
	v_exp_f32_e32 v76, v76
	v_exp_f32_e32 v82, v82
	v_add_f32_e32 v64, 1.0, v64
	v_add_f32_e32 v70, 1.0, v70
	v_add_f32_e32 v76, 1.0, v76
	v_add_f32_e32 v82, 1.0, v82
	v_rcp_f32_e32 v66, v64
	v_rcp_f32_e32 v72, v70
	v_rcp_f32_e32 v78, v76
	v_rcp_f32_e32 v84, v82
	v_fma_f32 v69, -v64, v66, 1.0
	v_fma_f32 v75, -v70, v72, 1.0
	v_fma_f32 v81, -v76, v78, 1.0
	v_fma_f32 v87, -v82, v84, 1.0
	v_fmac_f32_e32 v66, v69, v66
	v_fmac_f32_e32 v72, v75, v72
	v_fmac_f32_e32 v78, v81, v78
	v_fmac_f32_e32 v84, v87, v84
	v_fma_f32 v69, -v64, v66, 1.0
	v_mul_f32_e32 v88, 0xbfb8aa3b, v52
	v_fma_f32 v75, -v70, v72, 1.0
	v_mul_f32_e32 v94, 0xbfb8aa3b, v53
	v_fma_f32 v81, -v76, v78, 1.0
	v_mul_f32_e32 v100, 0xbfb8aa3b, v54
	v_fma_f32 v87, -v82, v84, 1.0
	v_mul_f32_e32 v106, 0xbfb8aa3b, v55
	v_fma_f32 v68, v69, v66, v66
	v_exp_f32_e32 v88, v88
	v_fma_f32 v74, v75, v72, v72
	v_exp_f32_e32 v94, v94
	v_fma_f32 v80, v81, v78, v78
	v_exp_f32_e32 v100, v100
	v_fma_f32 v86, v87, v84, v84
	v_exp_f32_e32 v106, v106
	v_fma_f32 v69, -v64, v68, 1.0
	v_add_f32_e32 v88, 1.0, v88
	v_fma_f32 v75, -v70, v74, 1.0
	v_add_f32_e32 v94, 1.0, v94
	v_fma_f32 v81, -v76, v80, 1.0
	v_add_f32_e32 v100, 1.0, v100
	v_fma_f32 v87, -v82, v86, 1.0
	v_add_f32_e32 v106, 1.0, v106
	v_fma_f32 v65, v69, v66, v68
	v_rcp_f32_e32 v90, v88
	v_fma_f32 v71, v75, v72, v74
	v_rcp_f32_e32 v96, v94
	v_fma_f32 v77, v81, v78, v80
	v_rcp_f32_e32 v102, v100
	v_fma_f32 v83, v87, v84, v86
	v_rcp_f32_e32 v108, v106
	v_fma_f32 v93, -v88, v90, 1.0
	v_fma_f32 v99, -v94, v96, 1.0
	v_fma_f32 v105, -v100, v102, 1.0
	v_fma_f32 v111, -v106, v108, 1.0
	v_fmac_f32_e32 v90, v93, v90
	v_fmac_f32_e32 v96, v99, v96
	v_fmac_f32_e32 v102, v105, v102
	v_fmac_f32_e32 v108, v111, v108
	v_div_fixup_f32 v65, v65, v64, 1.0
	v_div_fixup_f32 v71, v71, v70, 1.0
	v_div_fixup_f32 v77, v77, v76, 1.0
	v_div_fixup_f32 v83, v83, v82, 1.0
	v_mul_f32_e32 v65, v48, v65
	v_mul_f32_e32 v71, v49, v71
	v_mul_f32_e32 v77, v50, v77
	v_mul_f32_e32 v83, v51, v83
	v_mul_f32_e32 v65, v32, v65
	v_mul_f32_e32 v71, v33, v71
	v_mul_f32_e32 v77, v34, v77
	v_mul_f32_e32 v83, v35, v83
	v_cvt_pk_bf16_f32 v65, v65, v65
	v_cvt_pk_bf16_f32 v71, v71, v71
	v_cvt_pk_bf16_f32 v77, v77, v77
	v_cvt_pk_bf16_f32 v83, v83, v83
	ds_write_b16 v112, v65
	ds_write_b16 v112, v71 offset:64
	ds_write_b16 v112, v77 offset:128
	ds_write_b16 v112, v83 offset:192
	v_fma_f32 v93, -v88, v90, 1.0
	v_mul_f32_e32 v64, 0xbfb8aa3b, v56
	v_fma_f32 v99, -v94, v96, 1.0
	v_mul_f32_e32 v70, 0xbfb8aa3b, v57
	v_fma_f32 v105, -v100, v102, 1.0
	v_mul_f32_e32 v76, 0xbfb8aa3b, v58
	v_fma_f32 v111, -v106, v108, 1.0
	v_mul_f32_e32 v82, 0xbfb8aa3b, v59
	v_fma_f32 v92, v93, v90, v90
	v_exp_f32_e32 v64, v64
	v_fma_f32 v98, v99, v96, v96
	v_exp_f32_e32 v70, v70
	v_fma_f32 v104, v105, v102, v102
	v_exp_f32_e32 v76, v76
	v_fma_f32 v110, v111, v108, v108
	v_exp_f32_e32 v82, v82
	v_fma_f32 v93, -v88, v92, 1.0
	v_add_f32_e32 v64, 1.0, v64
	v_fma_f32 v99, -v94, v98, 1.0
	v_add_f32_e32 v70, 1.0, v70
	v_fma_f32 v105, -v100, v104, 1.0
	v_add_f32_e32 v76, 1.0, v76
	v_fma_f32 v111, -v106, v110, 1.0
	v_add_f32_e32 v82, 1.0, v82
	v_fma_f32 v89, v93, v90, v92
	v_rcp_f32_e32 v66, v64
	v_fma_f32 v95, v99, v96, v98
	v_rcp_f32_e32 v72, v70
	v_fma_f32 v101, v105, v102, v104
	v_rcp_f32_e32 v78, v76
	v_fma_f32 v107, v111, v108, v110
	v_rcp_f32_e32 v84, v82
	v_fma_f32 v69, -v64, v66, 1.0
	v_fma_f32 v75, -v70, v72, 1.0
	v_fma_f32 v81, -v76, v78, 1.0
	v_fma_f32 v87, -v82, v84, 1.0
	v_fmac_f32_e32 v66, v69, v66
	v_fmac_f32_e32 v72, v75, v72
	v_fmac_f32_e32 v78, v81, v78
	v_fmac_f32_e32 v84, v87, v84
	v_div_fixup_f32 v89, v89, v88, 1.0
	v_div_fixup_f32 v95, v95, v94, 1.0
	v_div_fixup_f32 v101, v101, v100, 1.0
	v_div_fixup_f32 v107, v107, v106, 1.0
	v_mul_f32_e32 v89, v52, v89
	v_mul_f32_e32 v95, v53, v95
	v_mul_f32_e32 v101, v54, v101
	v_mul_f32_e32 v107, v55, v107
	v_mul_f32_e32 v89, v36, v89
	v_mul_f32_e32 v95, v37, v95
	v_mul_f32_e32 v101, v38, v101
	v_mul_f32_e32 v107, v39, v107
	v_cvt_pk_bf16_f32 v89, v89, v89
	v_cvt_pk_bf16_f32 v95, v95, v95
	v_cvt_pk_bf16_f32 v101, v101, v101
	v_cvt_pk_bf16_f32 v107, v107, v107
	ds_write_b16 v112, v89 offset:512
	ds_write_b16 v112, v95 offset:576
	ds_write_b16 v112, v101 offset:640
	ds_write_b16 v112, v107 offset:704
	v_fma_f32 v69, -v64, v66, 1.0
	v_mul_f32_e32 v88, 0xbfb8aa3b, v60
	v_fma_f32 v75, -v70, v72, 1.0
	v_mul_f32_e32 v94, 0xbfb8aa3b, v61
	v_fma_f32 v81, -v76, v78, 1.0
	v_mul_f32_e32 v100, 0xbfb8aa3b, v62
	v_fma_f32 v87, -v82, v84, 1.0
	v_mul_f32_e32 v106, 0xbfb8aa3b, v63
	v_fma_f32 v68, v69, v66, v66
	v_exp_f32_e32 v88, v88
	v_fma_f32 v74, v75, v72, v72
	v_exp_f32_e32 v94, v94
	v_fma_f32 v80, v81, v78, v78
	v_exp_f32_e32 v100, v100
	v_fma_f32 v86, v87, v84, v84
	v_exp_f32_e32 v106, v106
	v_fma_f32 v69, -v64, v68, 1.0
	v_add_f32_e32 v88, 1.0, v88
	v_fma_f32 v75, -v70, v74, 1.0
	v_add_f32_e32 v94, 1.0, v94
	v_fma_f32 v81, -v76, v80, 1.0
	v_add_f32_e32 v100, 1.0, v100
	v_fma_f32 v87, -v82, v86, 1.0
	v_add_f32_e32 v106, 1.0, v106
	v_fma_f32 v65, v69, v66, v68
	v_rcp_f32_e32 v90, v88
	v_fma_f32 v71, v75, v72, v74
	v_rcp_f32_e32 v96, v94
	v_fma_f32 v77, v81, v78, v80
	v_rcp_f32_e32 v102, v100
	v_fma_f32 v83, v87, v84, v86
	v_rcp_f32_e32 v108, v106
	v_fma_f32 v93, -v88, v90, 1.0
	v_fma_f32 v99, -v94, v96, 1.0
	v_fma_f32 v105, -v100, v102, 1.0
	v_fma_f32 v111, -v106, v108, 1.0
	v_fmac_f32_e32 v90, v93, v90
	v_fmac_f32_e32 v96, v99, v96
	v_fmac_f32_e32 v102, v105, v102
	v_fmac_f32_e32 v108, v111, v108
	v_div_fixup_f32 v65, v65, v64, 1.0
	v_div_fixup_f32 v71, v71, v70, 1.0
	v_div_fixup_f32 v77, v77, v76, 1.0
	v_div_fixup_f32 v83, v83, v82, 1.0
	v_mul_f32_e32 v65, v56, v65
	v_mul_f32_e32 v71, v57, v71
	v_mul_f32_e32 v77, v58, v77
	v_mul_f32_e32 v83, v59, v83
	v_mul_f32_e32 v65, v40, v65
	v_mul_f32_e32 v71, v41, v71
	v_mul_f32_e32 v77, v42, v77
	v_mul_f32_e32 v83, v43, v83
	v_cvt_pk_bf16_f32 v65, v65, v65
	v_cvt_pk_bf16_f32 v71, v71, v71
	v_cvt_pk_bf16_f32 v77, v77, v77
	v_cvt_pk_bf16_f32 v83, v83, v83
	ds_write_b16 v112, v65 offset:1024
	ds_write_b16 v112, v71 offset:1088
	ds_write_b16 v112, v77 offset:1152
	ds_write_b16 v112, v83 offset:1216
	v_fma_f32 v93, -v88, v90, 1.0
	v_mul_f32_e32 v64, 0xbfb8aa3b, v16
	v_fma_f32 v99, -v94, v96, 1.0
	v_mul_f32_e32 v70, 0xbfb8aa3b, v17
	v_fma_f32 v105, -v100, v102, 1.0
	v_mul_f32_e32 v76, 0xbfb8aa3b, v18
	v_fma_f32 v111, -v106, v108, 1.0
	v_mul_f32_e32 v82, 0xbfb8aa3b, v19
	v_fma_f32 v92, v93, v90, v90
	v_exp_f32_e32 v64, v64
	v_fma_f32 v98, v99, v96, v96
	v_exp_f32_e32 v70, v70
	v_fma_f32 v104, v105, v102, v102
	v_exp_f32_e32 v76, v76
	v_fma_f32 v110, v111, v108, v108
	v_exp_f32_e32 v82, v82
	v_fma_f32 v93, -v88, v92, 1.0
	v_add_f32_e32 v64, 1.0, v64
	v_fma_f32 v99, -v94, v98, 1.0
	v_add_f32_e32 v70, 1.0, v70
	v_fma_f32 v105, -v100, v104, 1.0
	v_add_f32_e32 v76, 1.0, v76
	v_fma_f32 v111, -v106, v110, 1.0
	v_add_f32_e32 v82, 1.0, v82
	v_fma_f32 v89, v93, v90, v92
	v_rcp_f32_e32 v66, v64
	v_fma_f32 v95, v99, v96, v98
	v_rcp_f32_e32 v72, v70
	v_fma_f32 v101, v105, v102, v104
	v_rcp_f32_e32 v78, v76
	v_fma_f32 v107, v111, v108, v110
	v_rcp_f32_e32 v84, v82
	v_fma_f32 v69, -v64, v66, 1.0
	v_fma_f32 v75, -v70, v72, 1.0
	v_fma_f32 v81, -v76, v78, 1.0
	v_fma_f32 v87, -v82, v84, 1.0
	v_fmac_f32_e32 v66, v69, v66
	v_fmac_f32_e32 v72, v75, v72
	v_fmac_f32_e32 v78, v81, v78
	v_fmac_f32_e32 v84, v87, v84
	v_div_fixup_f32 v89, v89, v88, 1.0
	v_div_fixup_f32 v95, v95, v94, 1.0
	v_div_fixup_f32 v101, v101, v100, 1.0
	v_div_fixup_f32 v107, v107, v106, 1.0
	v_mul_f32_e32 v89, v60, v89
	v_mul_f32_e32 v95, v61, v95
	v_mul_f32_e32 v101, v62, v101
	v_mul_f32_e32 v107, v63, v107
	v_mul_f32_e32 v89, v44, v89
	v_mul_f32_e32 v95, v45, v95
	v_mul_f32_e32 v101, v46, v101
	v_mul_f32_e32 v107, v47, v107
	v_cvt_pk_bf16_f32 v89, v89, v89
	v_cvt_pk_bf16_f32 v95, v95, v95
	v_cvt_pk_bf16_f32 v101, v101, v101
	v_cvt_pk_bf16_f32 v107, v107, v107
	ds_write_b16 v112, v89 offset:1536
	ds_write_b16 v112, v95 offset:1600
	ds_write_b16 v112, v101 offset:1664
	ds_write_b16 v112, v107 offset:1728
	ds_read_b128 v[120:123], v113
	ds_read_b128 v[124:127], v113 offset:1024
	v_fma_f32 v69, -v64, v66, 1.0
	v_mul_f32_e32 v88, 0xbfb8aa3b, v20
	v_fma_f32 v75, -v70, v72, 1.0
	v_mul_f32_e32 v94, 0xbfb8aa3b, v21
	v_fma_f32 v81, -v76, v78, 1.0
	v_mul_f32_e32 v100, 0xbfb8aa3b, v22
	v_fma_f32 v87, -v82, v84, 1.0
	v_mul_f32_e32 v106, 0xbfb8aa3b, v23
	v_fma_f32 v68, v69, v66, v66
	v_exp_f32_e32 v88, v88
	v_fma_f32 v74, v75, v72, v72
	v_exp_f32_e32 v94, v94
	v_fma_f32 v80, v81, v78, v78
	v_exp_f32_e32 v100, v100
	v_fma_f32 v86, v87, v84, v84
	v_exp_f32_e32 v106, v106
	v_fma_f32 v69, -v64, v68, 1.0
	v_add_f32_e32 v88, 1.0, v88
	v_fma_f32 v75, -v70, v74, 1.0
	v_add_f32_e32 v94, 1.0, v94
	v_fma_f32 v81, -v76, v80, 1.0
	v_add_f32_e32 v100, 1.0, v100
	v_fma_f32 v87, -v82, v86, 1.0
	v_add_f32_e32 v106, 1.0, v106
	v_fma_f32 v65, v69, v66, v68
	v_rcp_f32_e32 v90, v88
	v_fma_f32 v71, v75, v72, v74
	v_rcp_f32_e32 v96, v94
	v_fma_f32 v77, v81, v78, v80
	v_rcp_f32_e32 v102, v100
	v_fma_f32 v83, v87, v84, v86
	v_rcp_f32_e32 v108, v106
	v_fma_f32 v93, -v88, v90, 1.0
	v_fma_f32 v99, -v94, v96, 1.0
	v_fma_f32 v105, -v100, v102, 1.0
	v_fma_f32 v111, -v106, v108, 1.0
	v_fmac_f32_e32 v90, v93, v90
	v_fmac_f32_e32 v96, v99, v96
	v_fmac_f32_e32 v102, v105, v102
	v_fmac_f32_e32 v108, v111, v108
	v_div_fixup_f32 v65, v65, v64, 1.0
	v_div_fixup_f32 v71, v71, v70, 1.0
	v_div_fixup_f32 v77, v77, v76, 1.0
	v_div_fixup_f32 v83, v83, v82, 1.0
	v_mul_f32_e32 v65, v16, v65
	v_mul_f32_e32 v71, v17, v71
	v_mul_f32_e32 v77, v18, v77
	v_mul_f32_e32 v83, v19, v83
	v_mul_f32_e32 v65, v0, v65
	v_mul_f32_e32 v71, v1, v71
	v_mul_f32_e32 v77, v2, v77
	v_mul_f32_e32 v83, v3, v83
	v_cvt_pk_bf16_f32 v65, v65, v65
	v_cvt_pk_bf16_f32 v71, v71, v71
	v_cvt_pk_bf16_f32 v77, v77, v77
	v_cvt_pk_bf16_f32 v83, v83, v83
	ds_write_b16 v112, v65
	ds_write_b16 v112, v71 offset:64
	ds_write_b16 v112, v77 offset:128
	ds_write_b16 v112, v83 offset:192
	v_fma_f32 v93, -v88, v90, 1.0
	v_mul_f32_e32 v64, 0xbfb8aa3b, v24
	v_fma_f32 v99, -v94, v96, 1.0
	v_mul_f32_e32 v70, 0xbfb8aa3b, v25
	v_fma_f32 v105, -v100, v102, 1.0
	v_mul_f32_e32 v76, 0xbfb8aa3b, v26
	v_fma_f32 v111, -v106, v108, 1.0
	v_mul_f32_e32 v82, 0xbfb8aa3b, v27
	v_fma_f32 v92, v93, v90, v90
	v_exp_f32_e32 v64, v64
	v_fma_f32 v98, v99, v96, v96
	v_exp_f32_e32 v70, v70
	v_fma_f32 v104, v105, v102, v102
	v_exp_f32_e32 v76, v76
	v_fma_f32 v110, v111, v108, v108
	v_exp_f32_e32 v82, v82
	v_fma_f32 v93, -v88, v92, 1.0
	v_add_f32_e32 v64, 1.0, v64
	v_fma_f32 v99, -v94, v98, 1.0
	v_add_f32_e32 v70, 1.0, v70
	v_fma_f32 v105, -v100, v104, 1.0
	v_add_f32_e32 v76, 1.0, v76
	v_fma_f32 v111, -v106, v110, 1.0
	v_add_f32_e32 v82, 1.0, v82
	v_fma_f32 v89, v93, v90, v92
	v_rcp_f32_e32 v66, v64
	v_fma_f32 v95, v99, v96, v98
	v_rcp_f32_e32 v72, v70
	v_fma_f32 v101, v105, v102, v104
	v_rcp_f32_e32 v78, v76
	v_fma_f32 v107, v111, v108, v110
	v_rcp_f32_e32 v84, v82
	v_fma_f32 v69, -v64, v66, 1.0
	v_fma_f32 v75, -v70, v72, 1.0
	v_fma_f32 v81, -v76, v78, 1.0
	v_fma_f32 v87, -v82, v84, 1.0
	v_fmac_f32_e32 v66, v69, v66
	v_fmac_f32_e32 v72, v75, v72
	v_fmac_f32_e32 v78, v81, v78
	v_fmac_f32_e32 v84, v87, v84
	s_waitcnt lgkmcnt(0)
	global_store_dwordx4 v114, v[120:123], s[98:99]
	s_add_u32 s98, s98, 0x16000
	s_addc_u32 s99, s99, 0
	global_store_dwordx4 v114, v[124:127], s[98:99]
	s_add_u32 s98, s98, 0x16000
	s_addc_u32 s99, s99, 0
	v_div_fixup_f32 v89, v89, v88, 1.0
	v_div_fixup_f32 v95, v95, v94, 1.0
	v_div_fixup_f32 v101, v101, v100, 1.0
	v_div_fixup_f32 v107, v107, v106, 1.0
	v_mul_f32_e32 v89, v20, v89
	v_mul_f32_e32 v95, v21, v95
	v_mul_f32_e32 v101, v22, v101
	v_mul_f32_e32 v107, v23, v107
	v_mul_f32_e32 v89, v4, v89
	v_mul_f32_e32 v95, v5, v95
	v_mul_f32_e32 v101, v6, v101
	v_mul_f32_e32 v107, v7, v107
	v_cvt_pk_bf16_f32 v89, v89, v89
	v_cvt_pk_bf16_f32 v95, v95, v95
	v_cvt_pk_bf16_f32 v101, v101, v101
	v_cvt_pk_bf16_f32 v107, v107, v107
	ds_write_b16 v112, v89 offset:512
	ds_write_b16 v112, v95 offset:576
	ds_write_b16 v112, v101 offset:640
	ds_write_b16 v112, v107 offset:704
	v_fma_f32 v69, -v64, v66, 1.0
	v_mul_f32_e32 v88, 0xbfb8aa3b, v28
	v_fma_f32 v75, -v70, v72, 1.0
	v_mul_f32_e32 v94, 0xbfb8aa3b, v29
	v_fma_f32 v81, -v76, v78, 1.0
	v_mul_f32_e32 v100, 0xbfb8aa3b, v30
	v_fma_f32 v87, -v82, v84, 1.0
	v_mul_f32_e32 v106, 0xbfb8aa3b, v31
	v_fma_f32 v68, v69, v66, v66
	v_exp_f32_e32 v88, v88
	v_fma_f32 v74, v75, v72, v72
	v_exp_f32_e32 v94, v94
	v_fma_f32 v80, v81, v78, v78
	v_exp_f32_e32 v100, v100
	v_fma_f32 v86, v87, v84, v84
	v_exp_f32_e32 v106, v106
	v_fma_f32 v69, -v64, v68, 1.0
	v_add_f32_e32 v88, 1.0, v88
	v_fma_f32 v75, -v70, v74, 1.0
	v_add_f32_e32 v94, 1.0, v94
	v_fma_f32 v81, -v76, v80, 1.0
	v_add_f32_e32 v100, 1.0, v100
	v_fma_f32 v87, -v82, v86, 1.0
	v_add_f32_e32 v106, 1.0, v106
	v_fma_f32 v65, v69, v66, v68
	v_rcp_f32_e32 v90, v88
	v_fma_f32 v71, v75, v72, v74
	v_rcp_f32_e32 v96, v94
	v_fma_f32 v77, v81, v78, v80
	v_rcp_f32_e32 v102, v100
	v_fma_f32 v83, v87, v84, v86
	v_rcp_f32_e32 v108, v106
	v_fma_f32 v93, -v88, v90, 1.0
	v_fma_f32 v99, -v94, v96, 1.0
	v_fma_f32 v105, -v100, v102, 1.0
	v_fma_f32 v111, -v106, v108, 1.0
	v_fmac_f32_e32 v90, v93, v90
	v_fmac_f32_e32 v96, v99, v96
	v_fmac_f32_e32 v102, v105, v102
	v_fmac_f32_e32 v108, v111, v108
	v_div_fixup_f32 v65, v65, v64, 1.0
	v_div_fixup_f32 v71, v71, v70, 1.0
	v_div_fixup_f32 v77, v77, v76, 1.0
	v_div_fixup_f32 v83, v83, v82, 1.0
	v_mul_f32_e32 v65, v24, v65
	v_mul_f32_e32 v71, v25, v71
	v_mul_f32_e32 v77, v26, v77
	v_mul_f32_e32 v83, v27, v83
	v_mul_f32_e32 v65, v8, v65
	v_mul_f32_e32 v71, v9, v71
	v_mul_f32_e32 v77, v10, v77
	v_mul_f32_e32 v83, v11, v83
	v_cvt_pk_bf16_f32 v65, v65, v65
	v_cvt_pk_bf16_f32 v71, v71, v71
	v_cvt_pk_bf16_f32 v77, v77, v77
	v_cvt_pk_bf16_f32 v83, v83, v83
	ds_write_b16 v112, v65 offset:1024
	ds_write_b16 v112, v71 offset:1088
	ds_write_b16 v112, v77 offset:1152
	ds_write_b16 v112, v83 offset:1216
	v_fma_f32 v93, -v88, v90, 1.0
	v_fma_f32 v99, -v94, v96, 1.0
	v_fma_f32 v105, -v100, v102, 1.0
	v_fma_f32 v111, -v106, v108, 1.0
	v_fma_f32 v92, v93, v90, v90
	v_fma_f32 v98, v99, v96, v96
	v_fma_f32 v104, v105, v102, v102
	v_fma_f32 v110, v111, v108, v108
	v_fma_f32 v93, -v88, v92, 1.0
	v_fma_f32 v99, -v94, v98, 1.0
	v_fma_f32 v105, -v100, v104, 1.0
	v_fma_f32 v111, -v106, v110, 1.0
	v_fma_f32 v89, v93, v90, v92
	v_fma_f32 v95, v99, v96, v98
	v_fma_f32 v101, v105, v102, v104
	v_fma_f32 v107, v111, v108, v110
	v_div_fixup_f32 v89, v89, v88, 1.0
	v_div_fixup_f32 v95, v95, v94, 1.0
	v_div_fixup_f32 v101, v101, v100, 1.0
	v_div_fixup_f32 v107, v107, v106, 1.0
	v_mul_f32_e32 v89, v28, v89
	v_mul_f32_e32 v95, v29, v95
	v_mul_f32_e32 v101, v30, v101
	v_mul_f32_e32 v107, v31, v107
	v_mul_f32_e32 v89, v12, v89
	v_mul_f32_e32 v95, v13, v95
	v_mul_f32_e32 v101, v14, v101
	v_mul_f32_e32 v107, v15, v107
	v_cvt_pk_bf16_f32 v89, v89, v89
	v_cvt_pk_bf16_f32 v95, v95, v95
	v_cvt_pk_bf16_f32 v101, v101, v101
	v_cvt_pk_bf16_f32 v107, v107, v107
	ds_write_b16 v112, v89 offset:1536
	ds_write_b16 v112, v95 offset:1600
	ds_write_b16 v112, v101 offset:1664
	ds_write_b16 v112, v107 offset:1728
	ds_read_b128 v[120:123], v113
	ds_read_b128 v[124:127], v113 offset:1024
	s_waitcnt lgkmcnt(0)
	global_store_dwordx4 v114, v[120:123], s[98:99]
	s_add_u32 s98, s98, 0x16000
	s_addc_u32 s99, s99, 0
	global_store_dwordx4 v114, v[124:127], s[98:99]
	s_add_u32 s98, s98, 0x16000
	s_addc_u32 s99, s99, 0
	s_add_i32 s47, s47, s92
	s_cmpk_gt_i32 s47, 0x107f
	s_cbranch_scc1 .LBB0_2292
